# attention tile loops: counted vmcnt waits instead of hipcc's vmcnt(0) drains after the V LDS-DMA issue (V loads now overlap QK and softmax)
# speedup vs baseline: 1.0034x; 1.0034x over previous
; #define LAS __attribute__((address_space(3)))
; template <bool ISA>
; __device__ __forceinline__ void attn_unit(LAS unsigned char* lds, const AttnArgs& T, int sc, int wave, int) {
;     ...
;     for (int kc = kc0; kc <= NPREV; ++kc) {
;         const bf16 *kp, *vp; int pitch;
;         ATT_TILE_PTRS(kc, kp, vp, pitch); (void)kp;
;         {
;             const unsigned voff = (unsigned)(((lane >> 3) * pitch + (((lane & 7) ^ ((lane >> 3) & 6)) * 8)) * 2);
; #pragma unroll
;             for (int i = 0; i < 8; ++i)
;                 __builtin_amdgcn_global_load_lds((const unsigned*)((const char*)(vp + (size_t)(8 * i) * pitch) + voff), (LAS unsigned*)(vst + i * 1024), 16, 0, 0);
;         }
;         bf16x8 pf[4][2];
; #pragma unroll
;         for (int qh = 0; qh < 2; ++qh) {
;             f32x4 s[4][2];
;             const LAS float* eb = ext + (768 + 32 * qh + fr - 64 * kc - 4 * fq);
; #pragma unroll
;             for (int kb = 0; kb < 4; ++kb)
; #pragma unroll
;                 for (int q2 = 0; q2 < 2; ++q2) {
;                     f32x4 c0 = (f32x4){0.f, 0.f, 0.f, 0.f};
;                     if (ISA) { const LAS float* e = eb + (16 * q2 - 16 * kb); c0 = (f32x4){e[0], e[-1], e[-2], e[-3]}; }
;                     f32x4 t = __builtin_amdgcn_mfma_f32_16x16x32_bf16(kf[kb][0], qf[2 * qh + q2][0], c0, 0, 0, 0);
;                     s[kb][q2] = __builtin_amdgcn_mfma_f32_16x16x32_bf16(kf[kb][1], qf[2 * qh + q2][1], t, 0, 0, 0);
;                 }
;             if (qh == 1) { const int kn = kc < NPREV ? kc + 1 : kc; const bf16 *kpn, *vpn; int pitchn; ATT_TILE_PTRS(kn, kpn, vpn, pitchn); (void)vpn; ATT_LOAD_K(kpn, pitchn); }
; #pragma unroll
;             for (int q2 = 0; q2 < 2; ++q2) {
;                 const int qb = 2 * qh + q2;
;                 float mx = fmaxf(fmaxf(s[0][q2][0], s[0][q2][1]), s[0][q2][2]);
;                 mx = fmaxf(fmaxf(mx, s[0][q2][3]), s[1][q2][0]); mx = fmaxf(fmaxf(mx, s[1][q2][1]), s[1][q2][2]); mx = fmaxf(fmaxf(mx, s[1][q2][3]), s[2][q2][0]);
;                 mx = fmaxf(fmaxf(mx, s[2][q2][1]), s[2][q2][2]); mx = fmaxf(fmaxf(mx, s[2][q2][3]), s[3][q2][0]); mx = fmaxf(fmaxf(mx, s[3][q2][1]), s[3][q2][2]); mx = fmaxf(mx, s[3][q2][3]);
;                 if (!__all(mx <= mrow[qb] + ATT_THR)) {
.LBB0_360:
	v_mul_lo_u32 v0, v202, s36
	v_or_b32_e32 v0, v0, v201
	v_lshl_add_u64 v[2:3], s[58:59], 0, v[0:1]
	s_mov_b32 m0, s92
	s_lshl_b32 s10, s36, 4
	global_load_lds_dwordx4 v0, s[58:59]
	v_lshl_add_u64 v[132:133], v[2:3], 0, s[10:11]
	s_mov_b32 m0, s95
	s_lshl_b32 s10, s36, 5
	global_load_lds_dwordx4 v[132:133], off
	v_lshl_add_u64 v[132:133], v[2:3], 0, s[10:11]
	s_mov_b32 m0, s96
	s_mul_i32 s10, s36, 48
	global_load_lds_dwordx4 v[132:133], off
	v_lshl_add_u64 v[132:133], v[2:3], 0, s[10:11]
	s_mov_b32 m0, s97
	s_lshl_b32 s10, s36, 6
	global_load_lds_dwordx4 v[132:133], off
	v_lshl_add_u64 v[132:133], v[2:3], 0, s[10:11]
	s_mov_b32 m0, s91
	s_mul_i32 s10, s36, 0x50
	global_load_lds_dwordx4 v[132:133], off
	v_lshl_add_u64 v[132:133], v[2:3], 0, s[10:11]
	s_mov_b32 m0, s72
	s_mul_i32 s10, s36, 0x60
	global_load_lds_dwordx4 v[132:133], off
	v_lshl_add_u64 v[132:133], v[2:3], 0, s[10:11]
	s_mov_b32 m0, s73
	s_mul_i32 s10, s36, 0x70
	global_load_lds_dwordx4 v[132:133], off
	v_lshl_add_u64 v[2:3], v[2:3], 0, s[10:11]
	s_mov_b32 m0, s4
	s_waitcnt vmcnt(7)
	v_mfma_f32_16x16x32_bf16 v[132:135], v[64:67], v[4:7], 0
	global_load_lds_dwordx4 v[2:3], off
	v_mfma_f32_16x16x32_bf16 v[140:143], v[56:59], v[4:7], 0
	v_mfma_f32_16x16x32_bf16 v[132:135], v[60:63], v[8:11], v[132:135]
	v_mfma_f32_16x16x32_bf16 v[148:151], v[48:51], v[4:7], 0
	v_mfma_f32_16x16x32_bf16 v[140:143], v[52:55], v[8:11], v[140:143]
	s_nop 5
	v_max_f32_e32 v0, v133, v133
	v_max_f32_e32 v2, v132, v132
	v_max_f32_e32 v0, v2, v0
	v_mfma_f32_16x16x32_bf16 v[152:155], v[40:43], v[4:7], 0
	v_max3_f32 v0, v0, v134, v135
	v_max3_f32 v0, v0, v140, v141
	v_max3_f32 v0, v0, v142, v143
	v_mfma_f32_16x16x32_bf16 v[156:159], v[44:47], v[8:11], v[148:151]
	v_add_f32_e32 v2, 0x40c00000, v208
	v_mfma_f32_16x16x32_bf16 v[136:139], v[64:67], v[12:15], 0
	v_mfma_f32_16x16x32_bf16 v[144:147], v[56:59], v[12:15], 0
	s_nop 4
	v_max3_f32 v0, v0, v156, v157
	v_max3_f32 v0, v0, v158, v159
	v_mfma_f32_16x16x32_bf16 v[148:151], v[48:51], v[12:15], 0
	v_mfma_f32_16x16x32_bf16 v[160:163], v[36:39], v[8:11], v[152:155]
	v_mfma_f32_16x16x32_bf16 v[152:155], v[40:43], v[12:15], 0
	v_mfma_f32_16x16x32_bf16 v[136:139], v[60:63], v[16:19], v[136:139]
	s_nop 5
	v_max3_f32 v0, v0, v160, v161
	v_max3_f32 v0, v0, v162, v163
	v_cmp_le_f32_e32 vcc, v0, v2
	v_mfma_f32_16x16x32_bf16 v[144:147], v[52:55], v[16:19], v[144:147]
	s_cmp_eq_u64 vcc, exec
	v_mfma_f32_16x16x32_bf16 v[148:151], v[44:47], v[16:19], v[148:151]
	v_mfma_f32_16x16x32_bf16 v[152:155], v[36:39], v[16:19], v[152:155]
	s_cbranch_scc1 .LBB0_362
	ds_bpermute_b32 v2, v197, v0
	v_max_f32_e32 v0, v0, v0
	s_waitcnt lgkmcnt(0)
	v_max_f32_e32 v2, v2, v2
	v_max_f32_e32 v0, v0, v2
	ds_bpermute_b32 v2, v198, v0
	s_waitcnt lgkmcnt(0)
	v_max3_f32 v2, v208, v0, v2
	v_sub_f32_e32 v0, v208, v2
	v_exp_f32_e32 v0, v0
	v_mov_b32_e32 v208, v2
	v_mul_f32_e32 v207, v207, v0
	v_pk_mul_f32 v[118:119], v[118:119], v[0:1] op_sel_hi:[1,0]
	v_pk_mul_f32 v[116:117], v[116:117], v[0:1] op_sel_hi:[1,0]
	v_pk_mul_f32 v[122:123], v[122:123], v[0:1] op_sel_hi:[1,0]
	v_pk_mul_f32 v[120:121], v[120:121], v[0:1] op_sel_hi:[1,0]
	v_pk_mul_f32 v[130:131], v[130:131], v[0:1] op_sel_hi:[1,0]
	v_pk_mul_f32 v[128:129], v[128:129], v[0:1] op_sel_hi:[1,0]
	v_pk_mul_f32 v[126:127], v[126:127], v[0:1] op_sel_hi:[1,0]
	v_pk_mul_f32 v[124:125], v[124:125], v[0:1] op_sel_hi:[1,0]

; #define LAS __attribute__((address_space(3)))
; __device__ __forceinline__ unsigned cvt_pk(float lo, float hi) { unsigned r; asm("v_cvt_pk_bf16_f32 %0, %1, %2" : "=v"(r) : "v"(lo), "v"(hi)); return r; }
; __device__ __forceinline__ float fexp2(float x) { return __builtin_amdgcn_exp2f(x); }
; template <bool ISA>
; __device__ __forceinline__ void attn_unit(LAS unsigned char* lds, const AttnArgs& T, int sc, int wave, int) {
;     ...
;                 const float mcur = mrow[qb];
;                 float ps = 0.f; float p[4][4];
; #pragma unroll
;                 for (int kb = 0; kb < 4; ++kb)
; #pragma unroll
;                     for (int j = 0; j < 4; ++j) { p[kb][j] = fexp2(s[kb][q2][j] - mcur); ps += p[kb][j]; }
;                 lrow[qb] += ps;
; #pragma unroll
;                 for (int kp2 = 0; kp2 < 2; ++kp2) {
;                     v4u w; w.x = cvt_pk(p[2 * kp2][0], p[2 * kp2][1]); w.y = cvt_pk(p[2 * kp2][2], p[2 * kp2][3]);
;                     w.z = cvt_pk(p[2 * kp2 + 1][0], p[2 * kp2 + 1][1]); w.w = cvt_pk(p[2 * kp2 + 1][2], p[2 * kp2 + 1][3]);
;                     pf[qb][kp2] = __builtin_bit_cast(bf16x8, w);
;                 }
;             }
;         }
;         asm volatile("s_waitcnt vmcnt(8)" ::: "memory");
;         __builtin_amdgcn_wave_barrier();
;         const int tq = (lane & 15) >> 2, tp = lane & 3;
; #pragma unroll
;         for (int kp2 = 0; kp2 < 2; ++kp2) {
;             bf16x8 vf[4];
; #pragma unroll
;             for (int db = 0; db < 4; ++db) {
;                 const int r8 = 4 * (fq & 1) + tq;
;                 LAS unsigned char* a0 = vst + (4 * kp2 + (fq >> 1)) * 1024 + r8 * 128 + (((2 * db + (tp >> 1)) ^ (r8 & 6)) * 16) + (tp & 1) * 8;
;                 const s16x4 lo = __builtin_bit_cast(s16x4, __builtin_amdgcn_ds_read_tr16_b64_v4i16((LAS s16x4*)a0));
;                 const s16x4 hi = __builtin_bit_cast(s16x4, __builtin_amdgcn_ds_read_tr16_b64_v4i16((LAS s16x4*)(a0 + 2048)));
;                 vf[db] = (bf16x8){lo[0], lo[1], lo[2], lo[3], hi[0], hi[1], hi[2], hi[3]};
;             }
; #pragma unroll
;             for (int qb = 0; qb < 4; ++qb)
; #pragma unroll
;                 for (int db = 0; db < 4; ++db) o[db][qb] = __builtin_amdgcn_mfma_f32_16x16x32_bf16(vf[db], pf[qb][kp2], o[db][qb], 0, 0, 0);
;         }
.LBB0_368:
	v_add_f32_e32 v0, 0, v0
	v_add_f32_e32 v0, v239, v0
	v_add_f32_e32 v0, v240, v0
	v_add_f32_e32 v0, v241, v0
	v_add_f32_e32 v0, v242, v0
	v_add_f32_e32 v0, v243, v0
	v_add_f32_e32 v0, v244, v0
	v_add_f32_e32 v0, v245, v0
	v_add_f32_e32 v0, v172, v0
	v_add_f32_e32 v0, v173, v0
	v_add_f32_e32 v0, v174, v0
	v_add_f32_e32 v0, v175, v0
	v_add_f32_e32 v0, v176, v0
	v_add_f32_e32 v0, v177, v0
	v_add_f32_e32 v0, v178, v0
	v_add_f32_e32 v0, v179, v0
	v_add_f32_e32 v193, v193, v0
	v_add_f32_e32 v0, 0, v223
	v_add_f32_e32 v0, v224, v0
	v_add_f32_e32 v0, v225, v0
	v_add_f32_e32 v0, v226, v0
	v_add_f32_e32 v0, v227, v0
	v_add_f32_e32 v0, v228, v0
	v_add_f32_e32 v0, v229, v0
	v_add_f32_e32 v0, v230, v0
	v_add_f32_e32 v0, v231, v0
	v_add_f32_e32 v0, v232, v0
	v_add_f32_e32 v0, v233, v0
	v_add_f32_e32 v0, v234, v0
	v_add_f32_e32 v0, v235, v0
	v_add_f32_e32 v0, v236, v0
	v_add_f32_e32 v0, v237, v0
	v_add_f32_e32 v0, v238, v0
	v_add_f32_e32 v195, v195, v0
	v_add_f32_e32 v0, 0, v2
	v_add_f32_e32 v0, v3, v0
	v_add_f32_e32 v0, v209, v0
	v_add_f32_e32 v0, v210, v0
	v_add_f32_e32 v0, v211, v0
	v_add_f32_e32 v0, v212, v0
	v_add_f32_e32 v0, v213, v0
	v_add_f32_e32 v0, v214, v0
	v_add_f32_e32 v0, v215, v0
	v_add_f32_e32 v0, v216, v0
	v_add_f32_e32 v0, v217, v0
	v_add_f32_e32 v0, v218, v0
	v_add_f32_e32 v0, v219, v0
	v_add_f32_e32 v0, v220, v0
	v_add_f32_e32 v0, v221, v0
	v_add_f32_e32 v0, v222, v0
	v_add_f32_e32 v207, v207, v0
	v_sub_f32_e32 v0, v152, v191
	v_exp_f32_e32 v0, v0
	v_sub_f32_e32 v3, v153, v191
	v_exp_f32_e32 v3, v3
	v_sub_f32_e32 v152, v154, v191
	v_exp_f32_e32 v152, v152
	v_sub_f32_e32 v153, v155, v191
	v_exp_f32_e32 v153, v153
	v_sub_f32_e32 v154, v160, v191
	v_add_f32_e32 v2, 0, v0
	v_exp_f32_e32 v154, v154
	v_sub_f32_e32 v155, v161, v191
	v_add_f32_e32 v2, v3, v2
	v_exp_f32_e32 v155, v155
	v_sub_f32_e32 v160, v162, v191
	v_add_f32_e32 v2, v152, v2
	v_exp_f32_e32 v172, v160
	v_sub_f32_e32 v160, v163, v191
	v_add_f32_e32 v2, v153, v2
	v_exp_f32_e32 v163, v160
	v_sub_f32_e32 v160, v168, v191
	v_add_f32_e32 v2, v154, v2
	v_exp_f32_e32 v168, v160
	v_sub_f32_e32 v160, v169, v191
	v_add_f32_e32 v2, v155, v2
	v_exp_f32_e32 v169, v160
	v_sub_f32_e32 v160, v170, v191
	v_add_f32_e32 v2, v172, v2
	v_exp_f32_e32 v170, v160
	v_sub_f32_e32 v160, v171, v191
	v_add_f32_e32 v2, v163, v2
	v_exp_f32_e32 v171, v160
	v_sub_f32_e32 v160, v164, v191
	v_add_f32_e32 v2, v168, v2
	v_exp_f32_e32 v164, v160
	v_sub_f32_e32 v160, v165, v191
	v_add_f32_e32 v2, v169, v2
	v_exp_f32_e32 v165, v160
	v_sub_f32_e32 v160, v166, v191
	v_add_f32_e32 v2, v170, v2
	v_exp_f32_e32 v166, v160
	v_sub_f32_e32 v160, v167, v191
	v_add_f32_e32 v2, v171, v2
	v_exp_f32_e32 v167, v160
	v_add_f32_e32 v2, v164, v2
	v_add_f32_e32 v2, v165, v2
	v_add_f32_e32 v2, v166, v2
	v_add_f32_e32 v2, v167, v2
	v_cvt_pk_bf16_f32 v161, v152, v153
	v_cvt_pk_bf16_f32 v162, v154, v155
	v_cvt_pk_bf16_f32 v163, v172, v163
	v_cvt_pk_bf16_f32 v152, v168, v169
	v_cvt_pk_bf16_f32 v153, v170, v171
	v_cvt_pk_bf16_f32 v154, v164, v165
	v_cvt_pk_bf16_f32 v155, v166, v167
	s_waitcnt vmcnt(8)
	ds_read_b64_tr_b16 v[164:165], v203
	ds_read_b64_tr_b16 v[166:167], v203 offset:2048
	ds_read_b64_tr_b16 v[168:169], v204
	ds_read_b64_tr_b16 v[170:171], v204 offset:2048
	ds_read_b64_tr_b16 v[172:173], v205
	ds_read_b64_tr_b16 v[174:175], v205 offset:2048
	ds_read_b64_tr_b16 v[176:177], v206
	ds_read_b64_tr_b16 v[178:179], v206 offset:2048
	v_cvt_pk_bf16_f32 v160, v0, v3
	s_waitcnt lgkmcnt(0)
	v_mfma_f32_16x16x32_bf16 v[116:119], v[164:167], v[140:143], v[116:119]
	s_add_i32 s90, s90, 64
	v_add_f32_e32 v190, v190, v2
	s_cmp_gt_u32 s88, 1
	v_mfma_f32_16x16x32_bf16 v[120:123], v[168:171], v[140:143], v[120:123]
	v_mfma_f32_16x16x32_bf16 v[128:131], v[172:175], v[140:143], v[128:131]
	v_mfma_f32_16x16x32_bf16 v[124:127], v[176:179], v[140:143], v[124:127]
	v_mfma_f32_16x16x32_bf16 v[100:103], v[164:167], v[144:147], v[100:103]
	v_mfma_f32_16x16x32_bf16 v[104:107], v[168:171], v[144:147], v[104:107]
	v_mfma_f32_16x16x32_bf16 v[112:115], v[172:175], v[144:147], v[112:115]
	v_mfma_f32_16x16x32_bf16 v[108:111], v[176:179], v[144:147], v[108:111]
	v_mfma_f32_16x16x32_bf16 v[84:87], v[164:167], v[156:159], v[84:87]
	v_mfma_f32_16x16x32_bf16 v[88:91], v[168:171], v[156:159], v[88:91]
	v_mfma_f32_16x16x32_bf16 v[96:99], v[172:175], v[156:159], v[96:99]
	v_mfma_f32_16x16x32_bf16 v[92:95], v[176:179], v[156:159], v[92:95]
	v_mfma_f32_16x16x32_bf16 v[68:71], v[164:167], v[160:163], v[68:71]
	v_mfma_f32_16x16x32_bf16 v[72:75], v[168:171], v[160:163], v[72:75]
	v_mfma_f32_16x16x32_bf16 v[80:83], v[172:175], v[160:163], v[80:83]
	v_mfma_f32_16x16x32_bf16 v[76:79], v[176:179], v[160:163], v[76:79]
	ds_read_b64_tr_b16 v[144:145], v203 offset:4096
	ds_read_b64_tr_b16 v[146:147], v203 offset:6144
	ds_read_b64_tr_b16 v[160:161], v204 offset:4096
	ds_read_b64_tr_b16 v[162:163], v204 offset:6144
	ds_read_b64_tr_b16 v[156:157], v205 offset:4096
	ds_read_b64_tr_b16 v[158:159], v205 offset:6144
	ds_read_b64_tr_b16 v[140:141], v206 offset:4096
	ds_read_b64_tr_b16 v[142:143], v206 offset:6144
	s_waitcnt lgkmcnt(6)
	v_mfma_f32_16x16x32_bf16 v[116:119], v[144:147], v[132:135], v[116:119]
	s_waitcnt lgkmcnt(4)
	v_mfma_f32_16x16x32_bf16 v[120:123], v[160:163], v[132:135], v[120:123]
	s_waitcnt lgkmcnt(2)
	v_mfma_f32_16x16x32_bf16 v[128:131], v[156:159], v[132:135], v[128:131]
	s_waitcnt lgkmcnt(0)
	v_mfma_f32_16x16x32_bf16 v[124:127], v[140:143], v[132:135], v[124:127]
	v_mfma_f32_16x16x32_bf16 v[100:103], v[144:147], v[136:139], v[100:103]
	v_mfma_f32_16x16x32_bf16 v[104:107], v[160:163], v[136:139], v[104:107]
	v_mfma_f32_16x16x32_bf16 v[112:115], v[156:159], v[136:139], v[112:115]
	v_mfma_f32_16x16x32_bf16 v[108:111], v[140:143], v[136:139], v[108:111]
	v_mfma_f32_16x16x32_bf16 v[84:87], v[144:147], v[148:151], v[84:87]
	v_mfma_f32_16x16x32_bf16 v[88:91], v[160:163], v[148:151], v[88:91]
	v_mfma_f32_16x16x32_bf16 v[96:99], v[156:159], v[148:151], v[96:99]
	v_mfma_f32_16x16x32_bf16 v[92:95], v[140:143], v[148:151], v[92:95]
	v_mfma_f32_16x16x32_bf16 v[68:71], v[144:147], v[152:155], v[68:71]
	v_mfma_f32_16x16x32_bf16 v[72:75], v[160:163], v[152:155], v[72:75]
	v_mfma_f32_16x16x32_bf16 v[80:83], v[156:159], v[152:155], v[80:83]
	v_mfma_f32_16x16x32_bf16 v[76:79], v[140:143], v[152:155], v[76:79]
	s_cbranch_scc1 .LBB0_371
	s_mov_b32 s88, s36
	s_branch .LBB0_356

; __device__ __forceinline__ float fexp2(float x) { return __builtin_amdgcn_exp2f(x); }
; template <bool ISA>
; __device__ __forceinline__ void attn_unit(LAS unsigned char* lds, const AttnArgs& T, int sc, int wave, int) {
;     ...
; #pragma unroll
;     for (int qb = 0; qb < 4; ++qb) {
;         float lt = lrow[qb]; lt += __shfl_xor(lt, 16); lt += __shfl_xor(lt, 32);
;         if (!ISA) lt += fexp2(sink2 - mrow[qb]);
;         const float inv = 1.0f / lt; float ss = 0.f;
; #pragma unroll
;         for (int db = 0; db < 4; ++db) { o[db][qb] = o[db][qb] * inv;
; #pragma unroll
;             for (int j = 0; j < 4; ++j) ss += o[db][qb][j] * o[db][qb][j]; }
;         ss += __shfl_xor(ss, 16); ss += __shfl_xor(ss, 32);
;         if (fq == 0) red[wave * 64 + 16 * qb + fr] = ss;
.LBB0_371:
	s_waitcnt vmcnt(0)
	ds_bpermute_b32 v0, v197, v207
	v_sub_f32_e32 v3, v182, v208
	v_exp_f32_e32 v3, v3
	s_waitcnt lgkmcnt(0)
	v_add_f32_e32 v0, v207, v0
	ds_bpermute_b32 v2, v198, v0
	s_waitcnt lgkmcnt(0)
	v_add_f32_e32 v0, v0, v2
	v_add_f32_e32 v0, v3, v0
	v_div_scale_f32 v2, s[8:9], v0, v0, 1.0
	v_rcp_f32_e32 v3, v2
	v_div_scale_f32 v4, vcc, 1.0, v0, 1.0
	v_cmp_gt_u32_e64 s[8:9], 16, v183
	v_fma_f32 v5, -v2, v3, 1.0
	v_fmac_f32_e32 v3, v5, v3
	v_mul_f32_e32 v5, v4, v3
	v_fma_f32 v6, -v2, v5, v4
	v_fmac_f32_e32 v5, v6, v3
	v_fma_f32 v2, -v2, v5, v4
	v_div_fmas_f32 v2, v2, v3, v5
	v_div_fixup_f32 v0, v2, v0, 1.0
	v_pk_mul_f32 v[20:21], v[116:117], v[0:1] op_sel_hi:[1,0]
	v_pk_mul_f32 v[18:19], v[118:119], v[0:1] op_sel_hi:[1,0]
	v_mul_f32_e32 v2, v21, v21
	v_fmac_f32_e32 v2, v20, v20
	v_fmac_f32_e32 v2, v18, v18
	v_pk_mul_f32 v[24:25], v[120:121], v[0:1] op_sel_hi:[1,0]
	v_fmac_f32_e32 v2, v19, v19
	v_fmac_f32_e32 v2, v24, v24
	v_pk_mul_f32 v[22:23], v[122:123], v[0:1] op_sel_hi:[1,0]
	v_fmac_f32_e32 v2, v25, v25
	v_fmac_f32_e32 v2, v22, v22
	v_pk_mul_f32 v[28:29], v[128:129], v[0:1] op_sel_hi:[1,0]
	v_fmac_f32_e32 v2, v23, v23
	v_fmac_f32_e32 v2, v28, v28
	v_pk_mul_f32 v[26:27], v[130:131], v[0:1] op_sel_hi:[1,0]
	v_fmac_f32_e32 v2, v29, v29
	v_fmac_f32_e32 v2, v26, v26
	v_fmac_f32_e32 v2, v27, v27
	v_pk_mul_f32 v[32:33], v[124:125], v[0:1] op_sel_hi:[1,0]
	v_pk_mul_f32 v[30:31], v[126:127], v[0:1] op_sel_hi:[1,0]
	v_fmac_f32_e32 v2, v32, v32
	v_fmac_f32_e32 v2, v33, v33
	v_fmac_f32_e32 v2, v30, v30
	v_fmac_f32_e32 v2, v31, v31
	ds_bpermute_b32 v0, v197, v2
	s_waitcnt lgkmcnt(0)
	v_add_f32_e32 v2, v2, v0
	ds_bpermute_b32 v3, v198, v2
	v_lshl_add_u32 v0, v183, 2, s93
	s_and_saveexec_b64 s[56:57], s[8:9]
	s_cbranch_execz .LBB0_373
	s_waitcnt lgkmcnt(0)
	v_add_f32_e32 v2, v2, v3
	ds_write_b32 v0, v2

; #define LAS __attribute__((address_space(3)))
; template <bool ISA>
; __device__ __forceinline__ void attn_unit(LAS unsigned char* lds, const AttnArgs& T, int sc, int wave, int) {
;     ...
;     for (int kc = kc0; kc <= NPREV; ++kc) {
;         const bf16 *kp, *vp; int pitch;
;         ATT_TILE_PTRS(kc, kp, vp, pitch); (void)kp;
;         {
;             const unsigned voff = (unsigned)(((lane >> 3) * pitch + (((lane & 7) ^ ((lane >> 3) & 6)) * 8)) * 2);
; #pragma unroll
;             for (int i = 0; i < 8; ++i)
;                 __builtin_amdgcn_global_load_lds((const unsigned*)((const char*)(vp + (size_t)(8 * i) * pitch) + voff), (LAS unsigned*)(vst + i * 1024), 16, 0, 0);
;         }
;         bf16x8 pf[4][2];
; #pragma unroll
;         for (int qh = 0; qh < 2; ++qh) {
;             f32x4 s[4][2];
;             const LAS float* eb = ext + (768 + 32 * qh + fr - 64 * kc - 4 * fq);
; #pragma unroll
;             for (int kb = 0; kb < 4; ++kb)
; #pragma unroll
;                 for (int q2 = 0; q2 < 2; ++q2) {
;                     f32x4 c0 = (f32x4){0.f, 0.f, 0.f, 0.f};
;                     if (ISA) { const LAS float* e = eb + (16 * q2 - 16 * kb); c0 = (f32x4){e[0], e[-1], e[-2], e[-3]}; }
;                     f32x4 t = __builtin_amdgcn_mfma_f32_16x16x32_bf16(kf[kb][0], qf[2 * qh + q2][0], c0, 0, 0, 0);
;                     s[kb][q2] = __builtin_amdgcn_mfma_f32_16x16x32_bf16(kf[kb][1], qf[2 * qh + q2][1], t, 0, 0, 0);
;                 }
;             if (qh == 1) { const int kn = kc < NPREV ? kc + 1 : kc; const bf16 *kpn, *vpn; int pitchn; ATT_TILE_PTRS(kn, kpn, vpn, pitchn); (void)vpn; ATT_LOAD_K(kpn, pitchn); }
; #pragma unroll
;             for (int q2 = 0; q2 < 2; ++q2) {
;                 const int qb = 2 * qh + q2;
;                 float mx = fmaxf(fmaxf(s[0][q2][0], s[0][q2][1]), s[0][q2][2]);
;                 mx = fmaxf(fmaxf(mx, s[0][q2][3]), s[1][q2][0]); mx = fmaxf(fmaxf(mx, s[1][q2][1]), s[1][q2][2]); mx = fmaxf(fmaxf(mx, s[1][q2][3]), s[2][q2][0]);
;                 mx = fmaxf(fmaxf(mx, s[2][q2][1]), s[2][q2][2]); mx = fmaxf(fmaxf(mx, s[2][q2][3]), s[3][q2][0]); mx = fmaxf(fmaxf(mx, s[3][q2][1]), s[3][q2][2]); mx = fmaxf(mx, s[3][q2][3]);
;                 if (!__all(mx <= mrow[qb] + ATT_THR)) {
.LBB0_394:
	v_mul_lo_u32 v0, v202, s36
	v_or_b32_e32 v0, v0, v201
	v_lshl_add_u64 v[2:3], s[66:67], 0, v[0:1]
	s_mov_b32 m0, s92
	s_lshl_b32 s10, s36, 4
	global_load_lds_dwordx4 v0, s[66:67]
	v_lshl_add_u64 v[132:133], v[2:3], 0, s[10:11]
	s_mov_b32 m0, s95
	s_lshl_b32 s10, s36, 5
	global_load_lds_dwordx4 v[132:133], off
	v_lshl_add_u64 v[132:133], v[2:3], 0, s[10:11]
	s_mov_b32 m0, s96
	s_mul_i32 s10, s36, 48
	global_load_lds_dwordx4 v[132:133], off
	v_lshl_add_u64 v[132:133], v[2:3], 0, s[10:11]
	s_mov_b32 m0, s97
	s_lshl_b32 s10, s36, 6
	global_load_lds_dwordx4 v[132:133], off
	v_lshl_add_u64 v[132:133], v[2:3], 0, s[10:11]
	s_mov_b32 m0, s91
	s_mul_i32 s10, s36, 0x50
	global_load_lds_dwordx4 v[132:133], off
	v_lshl_add_u64 v[132:133], v[2:3], 0, s[10:11]
	s_mov_b32 m0, s72
	s_mul_i32 s10, s36, 0x60
	global_load_lds_dwordx4 v[132:133], off
	v_lshl_add_u64 v[132:133], v[2:3], 0, s[10:11]
	s_mov_b32 m0, s73
	s_mul_i32 s10, s36, 0x70
	global_load_lds_dwordx4 v[132:133], off
	v_lshl_add_u64 v[2:3], v[2:3], 0, s[10:11]
	s_mov_b32 m0, s4
	v_add_u32_e32 v0, s94, v203
	global_load_lds_dwordx4 v[2:3], off
	v_add_u32_e32 v2, 0x10bfc, v0
	ds_read2_b32 v[2:3], v2 offset1:1
	v_add_u32_e32 v132, 0x10bf4, v0
	ds_read2_b32 v[132:133], v132 offset1:1
	v_add_u32_e32 v136, 0x10c34, v0
	ds_read2_b32 v[136:137], v136 offset1:1
	s_waitcnt lgkmcnt(0)
	v_mov_b32_e32 v149, v2
	v_add_u32_e32 v2, 0x10c3c, v0
	v_mov_b32_e32 v148, v3
	ds_read2_b32 v[2:3], v2 offset1:1
	v_add_u32_e32 v140, 0x10bb4, v0
	ds_read2_b32 v[140:141], v140 offset1:1
	v_add_u32_e32 v160, 0x10b74, v0
	v_mov_b32_e32 v150, v133
	s_waitcnt lgkmcnt(0)
	v_mov_b32_e32 v157, v2
	v_add_u32_e32 v2, 0x10bbc, v0
	v_mov_b32_e32 v156, v3
	ds_read2_b32 v[2:3], v2 offset1:1
	v_mov_b32_e32 v151, v132
	ds_read2_b32 v[160:161], v160 offset1:1
	v_add_u32_e32 v172, 0x10b34, v0
	s_waitcnt vmcnt(8)
	v_mfma_f32_16x16x32_bf16 v[132:135], v[64:67], v[4:7], v[148:151]
	s_waitcnt lgkmcnt(1)
	v_mov_b32_e32 v153, v2
	v_add_u32_e32 v2, 0x10b7c, v0
	v_mov_b32_e32 v152, v3
	ds_read2_b32 v[2:3], v2 offset1:1
	ds_read2_b32 v[176:177], v172 offset1:1
	v_mov_b32_e32 v154, v141
	v_mov_b32_e32 v155, v140
	v_mfma_f32_16x16x32_bf16 v[132:135], v[60:63], v[8:11], v[132:135]
	s_waitcnt lgkmcnt(1)
	v_mov_b32_e32 v165, v2
	v_add_u32_e32 v2, 0x10b3c, v0
	v_mov_b32_e32 v164, v3
	ds_read2_b32 v[2:3], v2 offset1:1
	v_mfma_f32_16x16x32_bf16 v[140:143], v[56:59], v[4:7], v[152:155]
	v_mov_b32_e32 v166, v161
	v_mov_b32_e32 v167, v160
	s_waitcnt lgkmcnt(1)
	v_mov_b32_e32 v174, v177
	s_waitcnt lgkmcnt(0)
	v_mov_b32_e32 v172, v3
	v_mfma_f32_16x16x32_bf16 v[160:163], v[48:51], v[4:7], v[164:167]
	v_mov_b32_e32 v173, v2
	v_mov_b32_e32 v175, v176
	v_max_f32_e32 v2, v133, v133
	v_mfma_f32_16x16x32_bf16 v[140:143], v[52:55], v[8:11], v[140:143]
	v_max_f32_e32 v3, v132, v132
	v_max_f32_e32 v2, v3, v2
	v_mov_b32_e32 v158, v137
	v_mfma_f32_16x16x32_bf16 v[172:175], v[40:43], v[4:7], v[172:175]
	v_mov_b32_e32 v159, v136
	v_max3_f32 v2, v2, v134, v135
	s_nop 1
	v_max3_f32 v2, v2, v140, v141
	v_mfma_f32_16x16x32_bf16 v[168:171], v[44:47], v[8:11], v[160:163]
	v_max3_f32 v2, v2, v142, v143
	v_add_f32_e32 v3, 0x40c00000, v212
	v_mfma_f32_16x16x32_bf16 v[136:139], v[64:67], v[12:15], v[156:159]
	v_mfma_f32_16x16x32_bf16 v[144:147], v[56:59], v[12:15], v[148:151]
	s_nop 3
	v_max3_f32 v2, v2, v168, v169
	v_max3_f32 v2, v2, v170, v171
	v_mfma_f32_16x16x32_bf16 v[160:163], v[48:51], v[12:15], v[152:155]
	v_mfma_f32_16x16x32_bf16 v[172:175], v[36:39], v[8:11], v[172:175]
	v_mfma_f32_16x16x32_bf16 v[164:167], v[40:43], v[12:15], v[164:167]
	v_mfma_f32_16x16x32_bf16 v[136:139], v[60:63], v[16:19], v[136:139]
	s_nop 5
	v_max3_f32 v2, v2, v172, v173
	v_max3_f32 v2, v2, v174, v175
	v_cmp_le_f32_e32 vcc, v2, v3
	v_mfma_f32_16x16x32_bf16 v[144:147], v[52:55], v[16:19], v[144:147]
	s_cmp_eq_u64 vcc, exec
	v_mfma_f32_16x16x32_bf16 v[160:163], v[44:47], v[16:19], v[160:163]
	v_mfma_f32_16x16x32_bf16 v[164:167], v[36:39], v[16:19], v[164:167]
	s_cbranch_scc1 .LBB0_396
	ds_bpermute_b32 v3, v197, v2
	v_max_f32_e32 v2, v2, v2
	s_waitcnt lgkmcnt(0)
	v_max_f32_e32 v3, v3, v3
	v_max_f32_e32 v2, v2, v3
	ds_bpermute_b32 v3, v198, v2
	s_waitcnt lgkmcnt(0)
	v_max3_f32 v3, v212, v2, v3
	v_sub_f32_e32 v2, v212, v3
	v_exp_f32_e32 v2, v2
	v_mov_b32_e32 v212, v3
	v_mul_f32_e32 v208, v208, v2
	v_pk_mul_f32 v[118:119], v[118:119], v[2:3] op_sel_hi:[1,0]
	v_pk_mul_f32 v[116:117], v[116:117], v[2:3] op_sel_hi:[1,0]
	v_pk_mul_f32 v[126:127], v[126:127], v[2:3] op_sel_hi:[1,0]
	v_pk_mul_f32 v[124:125], v[124:125], v[2:3] op_sel_hi:[1,0]
	v_pk_mul_f32 v[130:131], v[130:131], v[2:3] op_sel_hi:[1,0]
	v_pk_mul_f32 v[128:129], v[128:129], v[2:3] op_sel_hi:[1,0]
	v_pk_mul_f32 v[122:123], v[122:123], v[2:3] op_sel_hi:[1,0]
	v_pk_mul_f32 v[120:121], v[120:121], v[2:3] op_sel_hi:[1,0]

; #define LAS __attribute__((address_space(3)))
; template <bool ISA>
; __device__ __forceinline__ void attn_unit(LAS unsigned char* lds, const AttnArgs& T, int sc, int wave, int) {
;     ...
;     for (int kc = kc0; kc <= NPREV; ++kc) {
;         const bf16 *kp, *vp; int pitch;
;         ATT_TILE_PTRS(kc, kp, vp, pitch); (void)kp;
;         {
;             const unsigned voff = (unsigned)(((lane >> 3) * pitch + (((lane & 7) ^ ((lane >> 3) & 6)) * 8)) * 2);
; #pragma unroll
;             for (int i = 0; i < 8; ++i)
;                 __builtin_amdgcn_global_load_lds((const unsigned*)((const char*)(vp + (size_t)(8 * i) * pitch) + voff), (LAS unsigned*)(vst + i * 1024), 16, 0, 0);
;         }
;         bf16x8 pf[4][2];
; #pragma unroll
;         for (int qh = 0; qh < 2; ++qh) {
;             f32x4 s[4][2];
;             const LAS float* eb = ext + (768 + 32 * qh + fr - 64 * kc - 4 * fq);
; #pragma unroll
;             for (int kb = 0; kb < 4; ++kb)
; #pragma unroll
;                 for (int q2 = 0; q2 < 2; ++q2) {
;                     f32x4 c0 = (f32x4){0.f, 0.f, 0.f, 0.f};
;                     if (ISA) { const LAS float* e = eb + (16 * q2 - 16 * kb); c0 = (f32x4){e[0], e[-1], e[-2], e[-3]}; }
;                     f32x4 t = __builtin_amdgcn_mfma_f32_16x16x32_bf16(kf[kb][0], qf[2 * qh + q2][0], c0, 0, 0, 0);
;                     s[kb][q2] = __builtin_amdgcn_mfma_f32_16x16x32_bf16(kf[kb][1], qf[2 * qh + q2][1], t, 0, 0, 0);
;                 }
;             if (qh == 1) { const int kn = kc < NPREV ? kc + 1 : kc; const bf16 *kpn, *vpn; int pitchn; ATT_TILE_PTRS(kn, kpn, vpn, pitchn); (void)vpn; ATT_LOAD_K(kpn, pitchn); }
; #pragma unroll
;             for (int q2 = 0; q2 < 2; ++q2) {
;                 const int qb = 2 * qh + q2;
;                 float mx = fmaxf(fmaxf(s[0][q2][0], s[0][q2][1]), s[0][q2][2]);
;                 mx = fmaxf(fmaxf(mx, s[0][q2][3]), s[1][q2][0]); mx = fmaxf(fmaxf(mx, s[1][q2][1]), s[1][q2][2]); mx = fmaxf(fmaxf(mx, s[1][q2][3]), s[2][q2][0]);
;                 mx = fmaxf(fmaxf(mx, s[2][q2][1]), s[2][q2][2]); mx = fmaxf(fmaxf(mx, s[2][q2][3]), s[3][q2][0]); mx = fmaxf(fmaxf(mx, s[3][q2][1]), s[3][q2][2]); mx = fmaxf(mx, s[3][q2][3]);
;                 if (!__all(mx <= mrow[qb] + ATT_THR)) {
.LBB0_1096:
	v_mul_lo_u32 v0, v202, s46
	v_or_b32_e32 v0, v0, v201
	s_mov_b32 m0, s92
	v_lshl_add_u64 v[2:3], s[44:45], 0, v[0:1]
	s_lshl_b32 s10, s46, 4
	global_load_lds_dwordx4 v0, s[44:45]
	v_lshl_add_u64 v[148:149], v[2:3], 0, s[10:11]
	s_mov_b32 m0, s95
	s_lshl_b32 s10, s46, 5
	global_load_lds_dwordx4 v[148:149], off
	v_lshl_add_u64 v[148:149], v[2:3], 0, s[10:11]
	s_mov_b32 m0, s96
	s_mul_i32 s10, s46, 48
	global_load_lds_dwordx4 v[148:149], off
	v_lshl_add_u64 v[152:153], v[2:3], 0, s[10:11]
	s_mov_b32 m0, s97
	s_lshl_b32 s10, s46, 6
	global_load_lds_dwordx4 v[152:153], off
	v_lshl_add_u64 v[152:153], v[2:3], 0, s[10:11]
	s_mov_b32 m0, s91
	s_mul_i32 s10, s46, 0x50
	global_load_lds_dwordx4 v[152:153], off
	v_lshl_add_u64 v[152:153], v[2:3], 0, s[10:11]
	s_mov_b32 m0, s72
	s_mul_i32 s10, s46, 0x60
	global_load_lds_dwordx4 v[152:153], off
	v_lshl_add_u64 v[152:153], v[2:3], 0, s[10:11]
	s_mov_b32 m0, s73
	s_mul_i32 s10, s46, 0x70
	global_load_lds_dwordx4 v[152:153], off
	v_lshl_add_u64 v[2:3], v[2:3], 0, s[10:11]
	s_mov_b32 m0, s4
	s_waitcnt vmcnt(7)
	v_mfma_f32_16x16x32_bf16 v[132:135], v[64:67], v[4:7], 0
	global_load_lds_dwordx4 v[2:3], off
	v_mfma_f32_16x16x32_bf16 v[140:143], v[60:63], v[8:11], v[132:135]
	v_mfma_f32_16x16x32_bf16 v[132:135], v[64:67], v[12:15], 0
	v_mfma_f32_16x16x32_bf16 v[136:139], v[60:63], v[16:19], v[132:135]
	s_nop 5
	v_max_f32_e32 v0, v141, v141
	v_max_f32_e32 v2, v140, v140
	v_max_f32_e32 v0, v2, v0
	v_mfma_f32_16x16x32_bf16 v[132:135], v[56:59], v[4:7], 0
	v_max3_f32 v0, v0, v142, v143
	v_add_f32_e32 v2, 0x40c00000, v208
	v_mfma_f32_16x16x32_bf16 v[148:151], v[48:51], v[4:7], 0
	v_mfma_f32_16x16x32_bf16 v[132:135], v[52:55], v[8:11], v[132:135]
	v_mfma_f32_16x16x32_bf16 v[152:155], v[40:43], v[4:7], 0
	v_mfma_f32_16x16x32_bf16 v[156:159], v[44:47], v[8:11], v[148:151]
	s_nop 5
	v_max3_f32 v0, v0, v132, v133
	v_max3_f32 v0, v0, v134, v135
	v_mfma_f32_16x16x32_bf16 v[144:147], v[56:59], v[12:15], 0
	v_mfma_f32_16x16x32_bf16 v[148:151], v[48:51], v[12:15], 0
	v_max3_f32 v0, v0, v156, v157
	v_max3_f32 v0, v0, v158, v159
	v_mfma_f32_16x16x32_bf16 v[160:163], v[36:39], v[8:11], v[152:155]
	v_mfma_f32_16x16x32_bf16 v[152:155], v[40:43], v[12:15], 0
	v_mfma_f32_16x16x32_bf16 v[144:147], v[52:55], v[16:19], v[144:147]
	s_nop 5
	v_max3_f32 v0, v0, v160, v161
	v_max3_f32 v0, v0, v162, v163
	v_cmp_le_f32_e32 vcc, v0, v2
	v_mfma_f32_16x16x32_bf16 v[148:151], v[44:47], v[16:19], v[148:151]
	s_cmp_eq_u64 vcc, exec
	v_mfma_f32_16x16x32_bf16 v[152:155], v[36:39], v[16:19], v[152:155]
	s_cbranch_scc1 .LBB0_1098
	ds_bpermute_b32 v2, v197, v0
	v_max_f32_e32 v0, v0, v0
	s_waitcnt lgkmcnt(0)
	v_max_f32_e32 v2, v2, v2
	v_max_f32_e32 v0, v0, v2
	ds_bpermute_b32 v2, v198, v0
	s_waitcnt lgkmcnt(0)
	v_max3_f32 v2, v208, v0, v2
	v_sub_f32_e32 v0, v208, v2
	v_exp_f32_e32 v0, v0
	v_mov_b32_e32 v208, v2
	v_mul_f32_e32 v207, v207, v0
	v_pk_mul_f32 v[118:119], v[118:119], v[0:1] op_sel_hi:[1,0]
	v_pk_mul_f32 v[116:117], v[116:117], v[0:1] op_sel_hi:[1,0]
	v_pk_mul_f32 v[122:123], v[122:123], v[0:1] op_sel_hi:[1,0]
	v_pk_mul_f32 v[120:121], v[120:121], v[0:1] op_sel_hi:[1,0]
	v_pk_mul_f32 v[130:131], v[130:131], v[0:1] op_sel_hi:[1,0]
	v_pk_mul_f32 v[128:129], v[128:129], v[0:1] op_sel_hi:[1,0]
	v_pk_mul_f32 v[126:127], v[126:127], v[0:1] op_sel_hi:[1,0]
	v_pk_mul_f32 v[124:125], v[124:125], v[0:1] op_sel_hi:[1,0]

; #define LAS __attribute__((address_space(3)))
; __device__ __forceinline__ unsigned cvt_pk(float lo, float hi) { unsigned r; asm("v_cvt_pk_bf16_f32 %0, %1, %2" : "=v"(r) : "v"(lo), "v"(hi)); return r; }
; __device__ __forceinline__ float fexp2(float x) { return __builtin_amdgcn_exp2f(x); }
; template <bool ISA>
; __device__ __forceinline__ void attn_unit(LAS unsigned char* lds, const AttnArgs& T, int sc, int wave, int) {
;     ...
;                 const float mcur = mrow[qb];
;                 float ps = 0.f; float p[4][4];
; #pragma unroll
;                 for (int kb = 0; kb < 4; ++kb)
; #pragma unroll
;                     for (int j = 0; j < 4; ++j) { p[kb][j] = fexp2(s[kb][q2][j] - mcur); ps += p[kb][j]; }
;                 lrow[qb] += ps;
; #pragma unroll
;                 for (int kp2 = 0; kp2 < 2; ++kp2) {
;                     v4u w; w.x = cvt_pk(p[2 * kp2][0], p[2 * kp2][1]); w.y = cvt_pk(p[2 * kp2][2], p[2 * kp2][3]);
;                     w.z = cvt_pk(p[2 * kp2 + 1][0], p[2 * kp2 + 1][1]); w.w = cvt_pk(p[2 * kp2 + 1][2], p[2 * kp2 + 1][3]);
;                     pf[qb][kp2] = __builtin_bit_cast(bf16x8, w);
;                 }
;             }
;         }
;         asm volatile("s_waitcnt vmcnt(8)" ::: "memory");
;         __builtin_amdgcn_wave_barrier();
;         const int tq = (lane & 15) >> 2, tp = lane & 3;
; #pragma unroll
;         for (int kp2 = 0; kp2 < 2; ++kp2) {
;             bf16x8 vf[4];
; #pragma unroll
;             for (int db = 0; db < 4; ++db) {
;                 const int r8 = 4 * (fq & 1) + tq;
;                 LAS unsigned char* a0 = vst + (4 * kp2 + (fq >> 1)) * 1024 + r8 * 128 + (((2 * db + (tp >> 1)) ^ (r8 & 6)) * 16) + (tp & 1) * 8;
;                 const s16x4 lo = __builtin_bit_cast(s16x4, __builtin_amdgcn_ds_read_tr16_b64_v4i16((LAS s16x4*)a0));
;                 const s16x4 hi = __builtin_bit_cast(s16x4, __builtin_amdgcn_ds_read_tr16_b64_v4i16((LAS s16x4*)(a0 + 2048)));
;                 vf[db] = (bf16x8){lo[0], lo[1], lo[2], lo[3], hi[0], hi[1], hi[2], hi[3]};
;             }
; #pragma unroll
;             for (int qb = 0; qb < 4; ++qb)
; #pragma unroll
;                 for (int db = 0; db < 4; ++db) o[db][qb] = __builtin_amdgcn_mfma_f32_16x16x32_bf16(vf[db], pf[qb][kp2], o[db][qb], 0, 0, 0);
;         }
.LBB0_1104:
	v_add_f32_e32 v0, 0, v0
	v_add_f32_e32 v0, v239, v0
	v_add_f32_e32 v0, v240, v0
	v_add_f32_e32 v0, v241, v0
	v_add_f32_e32 v0, v242, v0
	v_add_f32_e32 v0, v243, v0
	v_add_f32_e32 v0, v244, v0
	v_add_f32_e32 v0, v245, v0
	v_add_f32_e32 v0, v172, v0
	v_add_f32_e32 v0, v173, v0
	v_add_f32_e32 v0, v174, v0
	v_add_f32_e32 v0, v175, v0
	v_add_f32_e32 v0, v176, v0
	v_add_f32_e32 v0, v177, v0
	v_add_f32_e32 v0, v178, v0
	v_add_f32_e32 v0, v179, v0
	v_add_f32_e32 v187, v187, v0
	v_add_f32_e32 v0, 0, v223
	v_add_f32_e32 v0, v224, v0
	v_add_f32_e32 v0, v225, v0
	v_add_f32_e32 v0, v226, v0
	v_add_f32_e32 v0, v227, v0
	v_add_f32_e32 v0, v228, v0
	v_add_f32_e32 v0, v229, v0
	v_add_f32_e32 v0, v230, v0
	v_add_f32_e32 v0, v231, v0
	v_add_f32_e32 v0, v232, v0
	v_add_f32_e32 v0, v233, v0
	v_add_f32_e32 v0, v234, v0
	v_add_f32_e32 v0, v235, v0
	v_add_f32_e32 v0, v236, v0
	v_add_f32_e32 v0, v237, v0
	v_add_f32_e32 v0, v238, v0
	v_add_f32_e32 v189, v189, v0
	v_add_f32_e32 v0, 0, v2
	v_add_f32_e32 v0, v3, v0
	v_add_f32_e32 v0, v209, v0
	v_add_f32_e32 v0, v210, v0
	v_add_f32_e32 v0, v211, v0
	v_add_f32_e32 v0, v212, v0
	v_add_f32_e32 v0, v213, v0
	v_add_f32_e32 v0, v214, v0
	v_add_f32_e32 v0, v215, v0
	v_add_f32_e32 v0, v216, v0
	v_add_f32_e32 v0, v217, v0
	v_add_f32_e32 v0, v218, v0
	v_add_f32_e32 v0, v219, v0
	v_add_f32_e32 v0, v220, v0
	v_add_f32_e32 v0, v221, v0
	v_add_f32_e32 v0, v222, v0
	v_add_f32_e32 v207, v207, v0
	v_sub_f32_e32 v0, v152, v185
	v_exp_f32_e32 v0, v0
	v_sub_f32_e32 v3, v153, v185
	v_exp_f32_e32 v3, v3
	v_sub_f32_e32 v152, v154, v185
	v_exp_f32_e32 v152, v152
	v_sub_f32_e32 v153, v155, v185
	v_exp_f32_e32 v153, v153
	v_sub_f32_e32 v154, v160, v185
	v_add_f32_e32 v2, 0, v0
	v_exp_f32_e32 v154, v154
	v_sub_f32_e32 v155, v161, v185
	v_add_f32_e32 v2, v3, v2
	v_exp_f32_e32 v155, v155
	v_sub_f32_e32 v160, v162, v185
	v_add_f32_e32 v2, v152, v2
	v_exp_f32_e32 v172, v160
	v_sub_f32_e32 v160, v163, v185
	v_add_f32_e32 v2, v153, v2
	v_exp_f32_e32 v163, v160
	v_sub_f32_e32 v160, v168, v185
	v_add_f32_e32 v2, v154, v2
	v_exp_f32_e32 v168, v160
	v_sub_f32_e32 v160, v169, v185
	v_add_f32_e32 v2, v155, v2
	v_exp_f32_e32 v169, v160
	v_sub_f32_e32 v160, v170, v185
	v_add_f32_e32 v2, v172, v2
	v_exp_f32_e32 v170, v160
	v_sub_f32_e32 v160, v171, v185
	v_add_f32_e32 v2, v163, v2
	v_exp_f32_e32 v171, v160
	v_sub_f32_e32 v160, v164, v185
	v_add_f32_e32 v2, v168, v2
	v_exp_f32_e32 v164, v160
	v_sub_f32_e32 v160, v165, v185
	v_add_f32_e32 v2, v169, v2
	v_exp_f32_e32 v165, v160
	v_sub_f32_e32 v160, v166, v185
	v_add_f32_e32 v2, v170, v2
	v_exp_f32_e32 v166, v160
	v_sub_f32_e32 v160, v167, v185
	v_add_f32_e32 v2, v171, v2
	v_exp_f32_e32 v167, v160
	v_add_f32_e32 v2, v164, v2
	v_add_f32_e32 v2, v165, v2
	v_add_f32_e32 v2, v166, v2
	v_add_f32_e32 v2, v167, v2
	v_cvt_pk_bf16_f32 v161, v152, v153
	v_cvt_pk_bf16_f32 v162, v154, v155
	v_cvt_pk_bf16_f32 v163, v172, v163
	v_cvt_pk_bf16_f32 v152, v168, v169
	v_cvt_pk_bf16_f32 v153, v170, v171
	v_cvt_pk_bf16_f32 v154, v164, v165
	v_cvt_pk_bf16_f32 v155, v166, v167
	s_waitcnt vmcnt(8)
	ds_read_b64_tr_b16 v[164:165], v203
	ds_read_b64_tr_b16 v[166:167], v203 offset:2048
	ds_read_b64_tr_b16 v[168:169], v204
	ds_read_b64_tr_b16 v[170:171], v204 offset:2048
	ds_read_b64_tr_b16 v[172:173], v205
	ds_read_b64_tr_b16 v[174:175], v205 offset:2048
	ds_read_b64_tr_b16 v[176:177], v206
	ds_read_b64_tr_b16 v[178:179], v206 offset:2048
	v_cvt_pk_bf16_f32 v160, v0, v3
	s_waitcnt lgkmcnt(0)
	v_mfma_f32_16x16x32_bf16 v[116:119], v[164:167], v[140:143], v[116:119]
	s_add_i32 s63, s63, 64
	v_add_f32_e32 v184, v184, v2
	s_cmp_gt_u32 s61, 1
	v_mfma_f32_16x16x32_bf16 v[120:123], v[168:171], v[140:143], v[120:123]
	v_mfma_f32_16x16x32_bf16 v[128:131], v[172:175], v[140:143], v[128:131]
	v_mfma_f32_16x16x32_bf16 v[124:127], v[176:179], v[140:143], v[124:127]
	v_mfma_f32_16x16x32_bf16 v[100:103], v[164:167], v[144:147], v[100:103]
	v_mfma_f32_16x16x32_bf16 v[104:107], v[168:171], v[144:147], v[104:107]
	v_mfma_f32_16x16x32_bf16 v[112:115], v[172:175], v[144:147], v[112:115]
	v_mfma_f32_16x16x32_bf16 v[108:111], v[176:179], v[144:147], v[108:111]
	v_mfma_f32_16x16x32_bf16 v[84:87], v[164:167], v[156:159], v[84:87]
	v_mfma_f32_16x16x32_bf16 v[88:91], v[168:171], v[156:159], v[88:91]
	v_mfma_f32_16x16x32_bf16 v[96:99], v[172:175], v[156:159], v[96:99]
	v_mfma_f32_16x16x32_bf16 v[92:95], v[176:179], v[156:159], v[92:95]
	v_mfma_f32_16x16x32_bf16 v[68:71], v[164:167], v[160:163], v[68:71]
	v_mfma_f32_16x16x32_bf16 v[72:75], v[168:171], v[160:163], v[72:75]
	v_mfma_f32_16x16x32_bf16 v[80:83], v[172:175], v[160:163], v[80:83]
	v_mfma_f32_16x16x32_bf16 v[76:79], v[176:179], v[160:163], v[76:79]
	ds_read_b64_tr_b16 v[144:145], v203 offset:4096
	ds_read_b64_tr_b16 v[146:147], v203 offset:6144
	ds_read_b64_tr_b16 v[160:161], v204 offset:4096
	ds_read_b64_tr_b16 v[162:163], v204 offset:6144
	ds_read_b64_tr_b16 v[156:157], v205 offset:4096
	ds_read_b64_tr_b16 v[158:159], v205 offset:6144
	ds_read_b64_tr_b16 v[140:141], v206 offset:4096
	ds_read_b64_tr_b16 v[142:143], v206 offset:6144
	s_waitcnt lgkmcnt(6)
	v_mfma_f32_16x16x32_bf16 v[116:119], v[144:147], v[132:135], v[116:119]
	s_waitcnt lgkmcnt(4)
	v_mfma_f32_16x16x32_bf16 v[120:123], v[160:163], v[132:135], v[120:123]
	s_waitcnt lgkmcnt(2)
	v_mfma_f32_16x16x32_bf16 v[128:131], v[156:159], v[132:135], v[128:131]
	s_waitcnt lgkmcnt(0)
	v_mfma_f32_16x16x32_bf16 v[124:127], v[140:143], v[132:135], v[124:127]
	v_mfma_f32_16x16x32_bf16 v[100:103], v[144:147], v[136:139], v[100:103]
	v_mfma_f32_16x16x32_bf16 v[104:107], v[160:163], v[136:139], v[104:107]
	v_mfma_f32_16x16x32_bf16 v[112:115], v[156:159], v[136:139], v[112:115]
	v_mfma_f32_16x16x32_bf16 v[108:111], v[140:143], v[136:139], v[108:111]
	v_mfma_f32_16x16x32_bf16 v[84:87], v[144:147], v[148:151], v[84:87]
	v_mfma_f32_16x16x32_bf16 v[88:91], v[160:163], v[148:151], v[88:91]
	v_mfma_f32_16x16x32_bf16 v[96:99], v[156:159], v[148:151], v[96:99]
	v_mfma_f32_16x16x32_bf16 v[92:95], v[140:143], v[148:151], v[92:95]
	v_mfma_f32_16x16x32_bf16 v[68:71], v[144:147], v[152:155], v[68:71]
	v_mfma_f32_16x16x32_bf16 v[72:75], v[160:163], v[152:155], v[72:75]
	v_mfma_f32_16x16x32_bf16 v[80:83], v[156:159], v[152:155], v[80:83]
	v_mfma_f32_16x16x32_bf16 v[76:79], v[140:143], v[152:155], v[76:79]
	s_cbranch_scc1 .LBB0_1107
	s_mov_b32 s61, s44
	s_branch .LBB0_1092

; __device__ __forceinline__ float fexp2(float x) { return __builtin_amdgcn_exp2f(x); }
; template <bool ISA>
; __device__ __forceinline__ void attn_unit(LAS unsigned char* lds, const AttnArgs& T, int sc, int wave, int) {
;     ...
; #pragma unroll
;     for (int qb = 0; qb < 4; ++qb) {
;         float lt = lrow[qb]; lt += __shfl_xor(lt, 16); lt += __shfl_xor(lt, 32);
;         if (!ISA) lt += fexp2(sink2 - mrow[qb]);
;         const float inv = 1.0f / lt; float ss = 0.f;
; #pragma unroll
;         for (int db = 0; db < 4; ++db) { o[db][qb] = o[db][qb] * inv;
; #pragma unroll
;             for (int j = 0; j < 4; ++j) ss += o[db][qb][j] * o[db][qb][j]; }
;         ss += __shfl_xor(ss, 16); ss += __shfl_xor(ss, 32);
;         if (fq == 0) red[wave * 64 + 16 * qb + fr] = ss;
.LBB0_1107:
	s_waitcnt vmcnt(0)
	ds_bpermute_b32 v0, v197, v207
	v_sub_f32_e32 v3, v182, v208
	v_exp_f32_e32 v3, v3
	s_waitcnt lgkmcnt(0)
	v_add_f32_e32 v0, v207, v0
	ds_bpermute_b32 v2, v198, v0
	s_waitcnt lgkmcnt(0)
	v_add_f32_e32 v0, v0, v2
	v_add_f32_e32 v0, v3, v0
	v_div_scale_f32 v2, s[8:9], v0, v0, 1.0
	v_rcp_f32_e32 v3, v2
	v_div_scale_f32 v4, vcc, 1.0, v0, 1.0
	v_cmp_gt_u32_e64 s[8:9], 16, v183
	v_fma_f32 v5, -v2, v3, 1.0
	v_fmac_f32_e32 v3, v5, v3
	v_mul_f32_e32 v5, v4, v3
	v_fma_f32 v6, -v2, v5, v4
	v_fmac_f32_e32 v5, v6, v3
	v_fma_f32 v2, -v2, v5, v4
	v_div_fmas_f32 v2, v2, v3, v5
	v_div_fixup_f32 v0, v2, v0, 1.0
	v_pk_mul_f32 v[20:21], v[116:117], v[0:1] op_sel_hi:[1,0]
	v_pk_mul_f32 v[18:19], v[118:119], v[0:1] op_sel_hi:[1,0]
	v_mul_f32_e32 v2, v21, v21
	v_fmac_f32_e32 v2, v20, v20
	v_fmac_f32_e32 v2, v18, v18
	v_pk_mul_f32 v[24:25], v[120:121], v[0:1] op_sel_hi:[1,0]
	v_fmac_f32_e32 v2, v19, v19
	v_fmac_f32_e32 v2, v24, v24
	v_pk_mul_f32 v[22:23], v[122:123], v[0:1] op_sel_hi:[1,0]
	v_fmac_f32_e32 v2, v25, v25
	v_fmac_f32_e32 v2, v22, v22
	v_pk_mul_f32 v[28:29], v[128:129], v[0:1] op_sel_hi:[1,0]
	v_fmac_f32_e32 v2, v23, v23
	v_fmac_f32_e32 v2, v28, v28
	v_pk_mul_f32 v[26:27], v[130:131], v[0:1] op_sel_hi:[1,0]
	v_fmac_f32_e32 v2, v29, v29
	v_fmac_f32_e32 v2, v26, v26
	v_fmac_f32_e32 v2, v27, v27
	v_pk_mul_f32 v[32:33], v[124:125], v[0:1] op_sel_hi:[1,0]
	v_pk_mul_f32 v[30:31], v[126:127], v[0:1] op_sel_hi:[1,0]
	v_fmac_f32_e32 v2, v32, v32
	v_fmac_f32_e32 v2, v33, v33
	v_fmac_f32_e32 v2, v30, v30
	v_fmac_f32_e32 v2, v31, v31
	ds_bpermute_b32 v0, v197, v2
	s_waitcnt lgkmcnt(0)
	v_add_f32_e32 v2, v2, v0
	ds_bpermute_b32 v3, v198, v2
	v_lshl_add_u32 v0, v183, 2, s93
	s_and_saveexec_b64 s[42:43], s[8:9]
	s_cbranch_execz .LBB0_1109
	s_waitcnt lgkmcnt(0)
	v_add_f32_e32 v2, v2, v3
	ds_write_b32 v0, v2

; #define LAS __attribute__((address_space(3)))
; template <bool ISA>
; __device__ __forceinline__ void attn_unit(LAS unsigned char* lds, const AttnArgs& T, int sc, int wave, int) {
;     ...
;     for (int kc = kc0; kc <= NPREV; ++kc) {
;         const bf16 *kp, *vp; int pitch;
;         ATT_TILE_PTRS(kc, kp, vp, pitch); (void)kp;
;         {
;             const unsigned voff = (unsigned)(((lane >> 3) * pitch + (((lane & 7) ^ ((lane >> 3) & 6)) * 8)) * 2);
; #pragma unroll
;             for (int i = 0; i < 8; ++i)
;                 __builtin_amdgcn_global_load_lds((const unsigned*)((const char*)(vp + (size_t)(8 * i) * pitch) + voff), (LAS unsigned*)(vst + i * 1024), 16, 0, 0);
;         }
;         bf16x8 pf[4][2];
; #pragma unroll
;         for (int qh = 0; qh < 2; ++qh) {
;             f32x4 s[4][2];
;             const LAS float* eb = ext + (768 + 32 * qh + fr - 64 * kc - 4 * fq);
; #pragma unroll
;             for (int kb = 0; kb < 4; ++kb)
; #pragma unroll
;                 for (int q2 = 0; q2 < 2; ++q2) {
;                     f32x4 c0 = (f32x4){0.f, 0.f, 0.f, 0.f};
;                     if (ISA) { const LAS float* e = eb + (16 * q2 - 16 * kb); c0 = (f32x4){e[0], e[-1], e[-2], e[-3]}; }
;                     f32x4 t = __builtin_amdgcn_mfma_f32_16x16x32_bf16(kf[kb][0], qf[2 * qh + q2][0], c0, 0, 0, 0);
;                     s[kb][q2] = __builtin_amdgcn_mfma_f32_16x16x32_bf16(kf[kb][1], qf[2 * qh + q2][1], t, 0, 0, 0);
;                 }
;             if (qh == 1) { const int kn = kc < NPREV ? kc + 1 : kc; const bf16 *kpn, *vpn; int pitchn; ATT_TILE_PTRS(kn, kpn, vpn, pitchn); (void)vpn; ATT_LOAD_K(kpn, pitchn); }
; #pragma unroll
;             for (int q2 = 0; q2 < 2; ++q2) {
;                 const int qb = 2 * qh + q2;
;                 float mx = fmaxf(fmaxf(s[0][q2][0], s[0][q2][1]), s[0][q2][2]);
;                 mx = fmaxf(fmaxf(mx, s[0][q2][3]), s[1][q2][0]); mx = fmaxf(fmaxf(mx, s[1][q2][1]), s[1][q2][2]); mx = fmaxf(fmaxf(mx, s[1][q2][3]), s[2][q2][0]);
;                 mx = fmaxf(fmaxf(mx, s[2][q2][1]), s[2][q2][2]); mx = fmaxf(fmaxf(mx, s[2][q2][3]), s[3][q2][0]); mx = fmaxf(fmaxf(mx, s[3][q2][1]), s[3][q2][2]); mx = fmaxf(mx, s[3][q2][3]);
;                 if (!__all(mx <= mrow[qb] + ATT_THR)) {
.LBB0_1130:
	v_mul_lo_u32 v0, v210, s43
	v_or_b32_e32 v0, v0, v209
	s_mov_b32 m0, s92
	v_lshl_add_u64 v[2:3], s[46:47], 0, v[0:1]
	s_lshl_b32 s10, s43, 4
	global_load_lds_dwordx4 v0, s[46:47]
	v_lshl_add_u64 v[132:133], v[2:3], 0, s[10:11]
	s_mov_b32 m0, s95
	s_lshl_b32 s10, s43, 5
	global_load_lds_dwordx4 v[132:133], off
	v_lshl_add_u64 v[132:133], v[2:3], 0, s[10:11]
	s_mov_b32 m0, s96
	s_mul_i32 s10, s43, 48
	global_load_lds_dwordx4 v[132:133], off
	v_lshl_add_u64 v[132:133], v[2:3], 0, s[10:11]
	s_mov_b32 m0, s97
	s_lshl_b32 s10, s43, 6
	global_load_lds_dwordx4 v[132:133], off
	v_lshl_add_u64 v[132:133], v[2:3], 0, s[10:11]
	s_mov_b32 m0, s91
	s_mul_i32 s10, s43, 0x50
	global_load_lds_dwordx4 v[132:133], off
	v_lshl_add_u64 v[132:133], v[2:3], 0, s[10:11]
	s_mov_b32 m0, s72
	s_mul_i32 s10, s43, 0x60
	global_load_lds_dwordx4 v[132:133], off
	v_lshl_add_u64 v[132:133], v[2:3], 0, s[10:11]
	s_mov_b32 m0, s73
	s_mul_i32 s10, s43, 0x70
	global_load_lds_dwordx4 v[132:133], off
	v_lshl_add_u64 v[2:3], v[2:3], 0, s[10:11]
	s_mov_b32 m0, s4
	v_add_u32_e32 v0, s66, v211
	global_load_lds_dwordx4 v[2:3], off
	v_add_u32_e32 v2, 0x10bfc, v0
	ds_read2_b32 v[2:3], v2 offset1:1
	v_add_u32_e32 v132, 0x10bf4, v0
	v_add_u32_e32 v134, 0x10c3c, v0
	v_add_u32_e32 v135, 0x10c34, v0
	ds_read2_b32 v[132:133], v132 offset1:1
	ds_read2_b32 v[136:137], v134 offset1:1
	ds_read2_b32 v[138:139], v135 offset1:1
	s_waitcnt lgkmcnt(0)
	v_mov_b32_e32 v141, v2
	v_add_u32_e32 v2, 0x10bbc, v0
	v_mov_b32_e32 v140, v3
	ds_read2_b32 v[2:3], v2 offset1:1
	v_add_u32_e32 v144, 0x10bb4, v0
	v_mov_b32_e32 v142, v133
	v_mov_b32_e32 v143, v132
	v_add_u32_e32 v146, 0x10b7c, v0
	v_add_u32_e32 v147, 0x10b74, v0
	ds_read2_b32 v[144:145], v144 offset1:1
	ds_read2_b32 v[152:153], v146 offset1:1
	ds_read2_b32 v[154:155], v147 offset1:1
	s_waitcnt vmcnt(8)
	v_mfma_f32_16x16x32_bf16 v[132:135], v[64:67], v[4:7], v[140:143]
	s_waitcnt lgkmcnt(3)
	v_mov_b32_e32 v177, v2
	v_add_u32_e32 v2, 0x10b3c, v0
	v_add_u32_e32 v168, 0x10b34, v0
	v_mov_b32_e32 v176, v3
	ds_read2_b32 v[2:3], v2 offset1:1
	ds_read2_b32 v[172:173], v168 offset1:1
	s_waitcnt lgkmcnt(4)
	v_mov_b32_e32 v178, v145
	v_mov_b32_e32 v179, v144
	v_mfma_f32_16x16x32_bf16 v[132:135], v[60:63], v[8:11], v[132:135]
	s_waitcnt lgkmcnt(3)
	v_mov_b32_e32 v160, v153
	v_mov_b32_e32 v161, v152
	s_waitcnt lgkmcnt(2)
	v_mov_b32_e32 v162, v155
	v_mfma_f32_16x16x32_bf16 v[144:147], v[56:59], v[4:7], v[176:179]
	v_mov_b32_e32 v163, v154
	s_waitcnt lgkmcnt(1)
	v_mov_b32_e32 v168, v3
	v_mov_b32_e32 v169, v2
	v_mfma_f32_16x16x32_bf16 v[152:155], v[48:51], v[4:7], v[160:163]
	s_waitcnt lgkmcnt(0)
	v_mov_b32_e32 v170, v173
	v_mov_b32_e32 v171, v172
	v_max_f32_e32 v2, v133, v133
	v_mfma_f32_16x16x32_bf16 v[144:147], v[52:55], v[8:11], v[144:147]
	v_max_f32_e32 v3, v132, v132
	v_max_f32_e32 v2, v3, v2
	v_mov_b32_e32 v156, v137
	v_mfma_f32_16x16x32_bf16 v[168:171], v[40:43], v[4:7], v[168:171]
	v_mov_b32_e32 v157, v136
	v_mov_b32_e32 v158, v139
	v_mov_b32_e32 v159, v138
	v_mfma_f32_16x16x32_bf16 v[164:167], v[44:47], v[8:11], v[152:155]
	v_max3_f32 v2, v2, v134, v135
	v_max3_f32 v2, v2, v144, v145
	v_max3_f32 v2, v2, v146, v147
	v_mfma_f32_16x16x32_bf16 v[136:139], v[64:67], v[12:15], v[156:159]
	v_add_f32_e32 v3, 0x40c00000, v220
	s_nop 2
	v_max3_f32 v2, v2, v164, v165
	v_max3_f32 v2, v2, v166, v167
	v_mfma_f32_16x16x32_bf16 v[148:151], v[56:59], v[12:15], v[140:143]
	v_mfma_f32_16x16x32_bf16 v[152:155], v[48:51], v[12:15], v[176:179]
	v_mfma_f32_16x16x32_bf16 v[168:171], v[36:39], v[8:11], v[168:171]
	v_mfma_f32_16x16x32_bf16 v[160:163], v[40:43], v[12:15], v[160:163]
	v_mfma_f32_16x16x32_bf16 v[136:139], v[60:63], v[16:19], v[136:139]
	s_nop 5
	v_max3_f32 v2, v2, v168, v169
	v_max3_f32 v2, v2, v170, v171
	v_cmp_le_f32_e32 vcc, v2, v3
	v_mfma_f32_16x16x32_bf16 v[148:151], v[52:55], v[16:19], v[148:151]
	s_cmp_eq_u64 vcc, exec
	v_mfma_f32_16x16x32_bf16 v[152:155], v[44:47], v[16:19], v[152:155]
	v_mfma_f32_16x16x32_bf16 v[160:163], v[36:39], v[16:19], v[160:163]
	s_cbranch_scc1 .LBB0_1132
	ds_bpermute_b32 v3, v197, v2
	v_max_f32_e32 v2, v2, v2
	s_waitcnt lgkmcnt(0)
	v_max_f32_e32 v3, v3, v3
	v_max_f32_e32 v2, v2, v3
	ds_bpermute_b32 v3, v198, v2
	s_waitcnt lgkmcnt(0)
	v_max3_f32 v3, v220, v2, v3
	v_sub_f32_e32 v2, v220, v3
	v_exp_f32_e32 v2, v2
	v_mov_b32_e32 v220, v3
	v_mul_f32_e32 v216, v216, v2
	v_pk_mul_f32 v[118:119], v[118:119], v[2:3] op_sel_hi:[1,0]
	v_pk_mul_f32 v[116:117], v[116:117], v[2:3] op_sel_hi:[1,0]
	v_pk_mul_f32 v[126:127], v[126:127], v[2:3] op_sel_hi:[1,0]
	v_pk_mul_f32 v[124:125], v[124:125], v[2:3] op_sel_hi:[1,0]
	v_pk_mul_f32 v[130:131], v[130:131], v[2:3] op_sel_hi:[1,0]
	v_pk_mul_f32 v[128:129], v[128:129], v[2:3] op_sel_hi:[1,0]
	v_pk_mul_f32 v[122:123], v[122:123], v[2:3] op_sel_hi:[1,0]
	v_pk_mul_f32 v[120:121], v[120:121], v[2:3] op_sel_hi:[1,0]
